# scan: next chunk's first LDS read burst issued at end of current chunk when loader counters already show it ready
# baseline (speedup 1.0000x reference)
.LBB0_493:
	s_or_b64 exec, exec, s[6:7]
	v_mov_b32_e32 v17, 0
	v_and_b32_e32 v18, 15, v0
	v_lshlrev_b32_e32 v23, 2, v1
	s_movk_i32 s14, 0x50
	s_waitcnt vmcnt(0)
	v_add_u32_e32 v16, 0xfffffe80, v0
	v_lshrrev_b32_e32 v0, 2, v3
	v_mov_b32_e32 v1, v17
	v_mad_u32_u24 v24, v18, s14, 0
	v_and_b32_e32 v29, 1, v16
	v_xor_b32_e32 v29, 1, v29
	v_lshrrev_b32_e32 v25, 1, v16
	v_lshl_add_u32 v25, v29, 4, v25
	v_lshlrev_b32_e32 v25, 2, v25
	v_add_u32_e32 v25, 0x8c0, v25
	v_lshlrev_b32_e32 v26, 2, v0
	s_lshl_b64 s[14:15], s[10:11], 21
	v_lshlrev_b64 v[0:1], 9, v[0:1]
	v_and_b32_e32 v27, 12, v2
	v_lshl_add_u64 v[0:1], s[14:15], 0, v[0:1]
	s_and_b32 s33, s72, 3
	v_lshlrev_b32_e32 v2, 1, v2
	v_lshl_or_b32 v0, s36, 7, v0
	s_lshl_b32 s33, s33, 5
	v_and_b32_e32 v2, 24, v2
	v_or3_b32 v0, v0, s33, v2
	v_lshl_add_u64 v[0:1], s[30:31], 0, v[0:1]
	s_mov_b64 s[34:35], 0x1d04000
	v_lshl_add_u64 v[0:1], v[0:1], 0, s[34:35]
	s_lshl_b64 s[34:35], s[10:11], 16
	s_lshl_b32 s33, s36, 2
	s_add_u32 s33, s30, s33
	s_addc_u32 s40, s31, 0
	s_add_u32 s34, s33, s34
	v_and_b32_e32 v22, 3, v6
	s_addc_u32 s35, s40, s35
	s_lshl_b64 s[10:11], s[10:11], 22
	v_lshlrev_b64 v[4:5], 10, v[6:7]
	v_lshlrev_b64 v[12:13], 2, v[8:9]
	v_lshlrev_b64 v[6:7], 9, v[6:7]
	v_lshlrev_b64 v[14:15], 1, v[8:9]
	v_lshlrev_b64 v[8:9], 10, v[10:11]
	v_lshlrev_b64 v[10:11], 9, v[10:11]
	v_and_b32_e32 v19, 12, v23
	v_lshl_add_u64 v[4:5], s[10:11], 0, v[4:5]
	v_lshl_add_u64 v[6:7], s[14:15], 0, v[6:7]
	v_lshl_add_u64 v[8:9], s[10:11], 0, v[8:9]
	v_lshl_add_u64 v[10:11], s[14:15], 0, v[10:11]
	s_movk_i32 s6, 0x7f
	s_movk_i32 s8, 0xa0
	v_lshl_add_u64 v[4:5], v[4:5], 0, v[12:13]
	v_lshl_add_u64 v[6:7], v[6:7], 0, v[14:15]
	v_lshl_add_u64 v[8:9], v[8:9], 0, v[12:13]
	v_lshl_add_u64 v[10:11], v[10:11], 0, v[14:15]
	v_lshl_or_b32 v12, v18, 10, s10
	v_add_u32_e32 v14, s37, v19
	v_cmp_lt_u32_e64 s[6:7], s6, v3
	v_cmp_gt_u32_e64 s[8:9], s8, v3
	v_lshl_add_u64 v[2:3], v[16:17], 4, s[34:35]
	s_mov_b64 s[34:35], 0x780200
	v_lshl_or_b32 v12, s36, 8, v12
	v_mov_b32_e32 v13, s11
	v_add_lshl_u32 v16, v14, v22, 2
	v_lshl_add_u64 v[2:3], v[2:3], 0, s[34:35]
	v_lshl_add_u64 v[4:5], s[30:31], 0, v[4:5]
	s_mov_b64 s[34:35], 0xc508000
	v_lshl_add_u64 v[8:9], s[30:31], 0, v[8:9]
	v_lshl_add_u64 v[12:13], v[12:13], 0, v[16:17]
	v_mov_b32_e32 v16, v17
	v_lshl_add_u64 v[4:5], v[4:5], 0, s[34:35]
	v_lshl_add_u64 v[6:7], s[30:31], 0, v[6:7]
	v_lshl_add_u64 v[8:9], v[8:9], 0, s[34:35]
	v_lshl_add_u64 v[10:11], s[30:31], 0, v[10:11]
	v_lshl_add_u64 v[12:13], s[30:31], 0, v[12:13]
	s_mov_b32 s58, 0
	s_mov_b32 s10, 0xaaaaaaaa
	s_mov_b32 s14, 0xcccccccc
	s_mov_b32 s34, 0xf000f
	s_mov_b32 s36, 0xf000f0
	s_mov_b32 s42, 0xf000f00
	s_mov_b32 s44, 0xf000f000
	s_mov_b32 s59, 0x4d00000
	s_mov_b32 s60, 0xd504000
	s_mov_b32 s61, 0xdd04000
	s_mov_b32 s62, 0xe504000
	s_mov_b32 s63, 0xed04000
	v_mul_u32_u24_e32 v27, 0x90, v27
	s_mov_b64 s[46:47], 0x4000
	s_mov_b64 s[48:49], 0x200
	s_mov_b64 s[50:51], 0x8000
	v_mov_b64_e32 v[18:19], v[16:17]
	v_mov_b32_e32 v28, v17
	v_mov_b32_e32 v60, 0x1f000
	v_mov_b32_e32 v64, 0
	v_mov_b32_e32 v65, 0
	v_mov_b32_e32 v66, 0
	v_mov_b32_e32 v67, 0
	ds_write_b128 v60, v[64:67]
	ds_write_b128 v60, v[64:67] offset:16
	s_waitcnt lgkmcnt(0)
	s_mov_b32 s33, 0
	s_barrier
	s_branch .LBB0_496

.LBB0_496:
	s_and_b32 s54, s58, 1
	s_and_saveexec_b64 s[40:41], s[4:5]
	s_xor_b64 s[52:53], exec, s[40:41]
	s_cbranch_execz .LBB0_498
	s_mov_b32 s11, s10
	s_mov_b32 s15, s14
	s_mov_b32 s35, s34
	s_mov_b32 s37, s36
	s_mov_b32 s43, s42
	s_mov_b32 s45, s44
	v_mov_b32_e32 v220, 0x1f000
	v_add_u32_e32 v221, 0x1f010, v23
	v_mov_b32_e32 v222, 1
	s_cmp_eq_u32 s33, 1
	s_cbranch_scc1 .Lpf_skip0
	s_cmp_eq_u32 s58, 0
	s_cbranch_scc1 .Lrdy_ok0
	s_waitcnt lgkmcnt(0)
	s_movk_i32 s40, 0x4000
.Lrdy_chk0:
	v_min3_u32 v228, v224, v225, v226
	v_min_u32_e32 v228, v228, v227
	s_nop 0
	v_readfirstlane_b32 s41, v228
	s_cmp_ge_u32 s41, s58
	s_cbranch_scc1 .Lrdy_ok0
	s_sub_u32 s40, s40, 1
	s_cmp_eq_u32 s40, 0
	s_cbranch_scc1 .Lrdy_ok0
	s_sleep 1
	ds_read_b128 v[224:227], v220
	s_waitcnt lgkmcnt(0)
	s_branch .Lrdy_chk0
.Lrdy_ok0:
	s_mul_i32 s40, s54, 0xa000
	s_mul_i32 s41, s54, 0xa00
	s_add_i32 s41, s41, 0x14000
	v_add_u32_e32 v29, s40, v24
	v_add_u32_e32 v31, v23, v22
	v_mul_u32_u24_e32 v31, 0x90, v31
	v_mov_b32_e32 v30, s41
	v_add_u32_e32 v31, s41, v31
	ds_read_b128 v[44:47], v29 offset:48
	ds_read_b128 v[64:67], v29 offset:1328
	ds_read_b128 v[40:43], v29 offset:32
	ds_read_b128 v[112:115], v31 offset:0
	ds_read_b128 v[32:35], v29 offset:0
	ds_read_b128 v[120:123], v30 offset:2304
	ds_read_b128 v[48:51], v29 offset:64
	ds_read_b128 v[60:63], v29 offset:1312
	ds_read_b128 v[52:55], v29 offset:1280
	ds_read_b128 v[36:39], v29 offset:16
	ds_read_b128 v[68:71], v29 offset:1344
	ds_read_b128 v[56:59], v29 offset:1296
.Lpf_skip0:
	s_cmp_eq_u32 s58, 0
	s_cbranch_scc1 .Lscan_tail_skip0
	v_add_f32_e32 v206, v144, v145
	v_add_f32_e32 v207, v146, v147
	v_cndmask_b32_e64 v208, v204, v205, s[10:11]
	v_cndmask_b32_e64 v209, v205, v204, s[10:11]
	v_cndmask_b32_e64 v210, v206, v207, s[10:11]
	v_cndmask_b32_e64 v211, v207, v206, s[10:11]
	v_add_f32_dpp v212, v209, v208 quad_perm:[1,0,3,2] row_mask:0xf bank_mask:0xf bound_ctrl:1
	s_nop 0
	v_add_f32_dpp v213, v211, v210 quad_perm:[1,0,3,2] row_mask:0xf bank_mask:0xf bound_ctrl:1
	v_cndmask_b32_e64 v214, v212, v213, s[14:15]
	v_cndmask_b32_e64 v215, v213, v212, s[14:15]
	s_nop 1
	v_add_f32_dpp v216, v215, v214 quad_perm:[2,3,0,1] row_mask:0xf bank_mask:0xf bound_ctrl:1
	s_nop 1
	v_add_f32_dpp v216, v216, v216 row_ror:8 row_mask:0xf bank_mask:0xf bound_ctrl:1
	s_nop 1
	v_add_f32_dpp v216, v216, v216 row_ror:4 row_mask:0xf bank_mask:0xf bound_ctrl:1
	v_cndmask_b32_e64 v28, v28, v216, s[44:45]
	v_add_co_u32_e32 v218, vcc, 0x4cfc000, v12
	s_nop 1
	v_addc_co_u32_e32 v219, vcc, 0, v13, vcc
	global_store_dword v[218:219], v28, off
.Lscan_tail_skip0:
	s_waitcnt lgkmcnt(7)
	v_pk_mul_f32 v[132:133], v[16:17], v[44:45]
	v_pk_mul_f32 v[134:135], v[16:17], v[64:65]
	v_pk_fma_f32 v[132:133], v[18:19], v[46:47], v[132:133]
	v_pk_fma_f32 v[134:135], v[18:19], v[66:67], v[134:135]
	v_pk_mul_f32 v[136:137], v[112:113], v[40:41] op_sel_hi:[0,1]
	v_add_f32_e32 v148, v132, v133
	v_add_f32_e32 v149, v134, v135
	v_pk_mul_f32 v[138:139], v[112:113], v[42:43] op_sel_hi:[0,1]
	v_add_f32_dpp v148, v148, v148 quad_perm:[1,0,3,2] row_mask:0xf bank_mask:0xf bound_ctrl:1
	v_add_f32_dpp v149, v149, v149 quad_perm:[1,0,3,2] row_mask:0xf bank_mask:0xf bound_ctrl:1
	v_pk_fma_f32 v[136:137], v[16:17], v[32:33], v[136:137]
	v_add_f32_dpp v148, v148, v148 quad_perm:[2,3,0,1] row_mask:0xf bank_mask:0xf bound_ctrl:1
	v_add_f32_dpp v149, v149, v149 quad_perm:[2,3,0,1] row_mask:0xf bank_mask:0xf bound_ctrl:1
	v_pk_fma_f32 v[138:139], v[18:19], v[34:35], v[138:139]
	v_add_f32_dpp v148, v148, v148 row_half_mirror row_mask:0xf bank_mask:0xf bound_ctrl:1
	v_add_f32_dpp v149, v149, v149 row_half_mirror row_mask:0xf bank_mask:0xf bound_ctrl:1
	ds_read_b128 v[84:87], v29 offset:2608
	ds_read_b128 v[104:107], v29 offset:3888
	ds_read_b128 v[80:83], v29 offset:2592
	ds_read_b128 v[72:75], v29 offset:2560
	ds_read_b128 v[88:91], v29 offset:2624
	ds_read_b128 v[100:103], v29 offset:3872
	ds_read_b128 v[92:95], v29 offset:3840
	ds_read_b128 v[76:79], v29 offset:2576
	ds_read_b128 v[108:111], v29 offset:3904
	ds_read_b128 v[96:99], v29 offset:3856
	s_waitcnt lgkmcnt(10)
	v_pk_mul_f32 v[140:141], v[112:113], v[60:61] op_sel:[1,0] op_sel_hi:[1,1]
	v_add_f32_dpp v148, v148, v148 row_mirror row_mask:0xf bank_mask:0xf bound_ctrl:1
	v_add_f32_dpp v149, v149, v149 row_mirror row_mask:0xf bank_mask:0xf bound_ctrl:1
	v_pk_mul_f32 v[142:143], v[112:113], v[62:63] op_sel:[1,0] op_sel_hi:[1,1]
	v_fmac_f32_e32 v149, v112, v120
	v_pk_fma_f32 v[16:17], v[48:49], v[148:149], v[136:137] op_sel_hi:[1,0,1]
	v_pk_fma_f32 v[18:19], v[50:51], v[148:149], v[138:139] op_sel_hi:[1,0,1]
	v_pk_fma_f32 v[140:141], v[16:17], v[52:53], v[140:141]
	v_pk_mul_f32 v[144:145], v[16:17], v[36:37]
	v_pk_fma_f32 v[142:143], v[18:19], v[54:55], v[142:143]
	v_pk_fma_f32 v[144:145], v[18:19], v[38:39], v[144:145]
	v_pk_fma_f32 v[16:17], v[68:69], v[148:149], v[140:141] op_sel:[0,1,0] op_sel_hi:[1,1,1]
	v_pk_fma_f32 v[18:19], v[70:71], v[148:149], v[142:143] op_sel:[0,1,0] op_sel_hi:[1,1,1]
	v_pk_mul_f32 v[146:147], v[16:17], v[56:57]
	v_pk_fma_f32 v[146:147], v[18:19], v[58:59], v[146:147]
	s_waitcnt lgkmcnt(6)
	v_pk_mul_f32 v[132:133], v[16:17], v[84:85]
	v_pk_mul_f32 v[134:135], v[16:17], v[104:105]
	v_add_f32_e32 v200, v144, v145
	v_pk_fma_f32 v[132:133], v[18:19], v[86:87], v[132:133]
	v_pk_fma_f32 v[134:135], v[18:19], v[106:107], v[134:135]
	v_add_f32_e32 v201, v146, v147
	v_pk_mul_f32 v[136:137], v[114:115], v[80:81] op_sel_hi:[0,1]
	v_add_f32_e32 v148, v132, v133
	v_add_f32_e32 v149, v134, v135
	v_pk_mul_f32 v[138:139], v[114:115], v[82:83] op_sel_hi:[0,1]
	v_add_f32_dpp v148, v148, v148 quad_perm:[1,0,3,2] row_mask:0xf bank_mask:0xf bound_ctrl:1
	v_add_f32_dpp v149, v149, v149 quad_perm:[1,0,3,2] row_mask:0xf bank_mask:0xf bound_ctrl:1
	v_pk_fma_f32 v[136:137], v[16:17], v[72:73], v[136:137]
	v_add_f32_dpp v148, v148, v148 quad_perm:[2,3,0,1] row_mask:0xf bank_mask:0xf bound_ctrl:1
	v_add_f32_dpp v149, v149, v149 quad_perm:[2,3,0,1] row_mask:0xf bank_mask:0xf bound_ctrl:1
	v_pk_fma_f32 v[138:139], v[18:19], v[74:75], v[138:139]
	v_add_f32_dpp v148, v148, v148 row_half_mirror row_mask:0xf bank_mask:0xf bound_ctrl:1
	v_add_f32_dpp v149, v149, v149 row_half_mirror row_mask:0xf bank_mask:0xf bound_ctrl:1
	ds_read_b128 v[44:47], v29 offset:5168
	ds_read_b128 v[64:67], v29 offset:6448
	ds_read_b128 v[40:43], v29 offset:5152
	ds_read_b128 v[116:119], v31 offset:16
	ds_read_b128 v[32:35], v29 offset:5120
	ds_read_b128 v[48:51], v29 offset:5184
	ds_read_b128 v[60:63], v29 offset:6432
	ds_read_b128 v[52:55], v29 offset:6400
	ds_read_b128 v[36:39], v29 offset:5136
	ds_read_b128 v[68:71], v29 offset:6464
	ds_read_b128 v[56:59], v29 offset:6416
	s_waitcnt lgkmcnt(11)
	v_pk_mul_f32 v[140:141], v[114:115], v[100:101] op_sel:[1,0] op_sel_hi:[1,1]
	v_add_f32_dpp v148, v148, v148 row_mirror row_mask:0xf bank_mask:0xf bound_ctrl:1
	v_add_f32_dpp v149, v149, v149 row_mirror row_mask:0xf bank_mask:0xf bound_ctrl:1
	v_pk_mul_f32 v[142:143], v[114:115], v[102:103] op_sel:[1,0] op_sel_hi:[1,1]
	v_fmac_f32_e32 v149, v114, v121
	v_pk_fma_f32 v[16:17], v[88:89], v[148:149], v[136:137] op_sel_hi:[1,0,1]
	v_pk_fma_f32 v[18:19], v[90:91], v[148:149], v[138:139] op_sel_hi:[1,0,1]
	v_pk_fma_f32 v[140:141], v[16:17], v[92:93], v[140:141]
	v_pk_mul_f32 v[144:145], v[16:17], v[76:77]
	v_pk_fma_f32 v[142:143], v[18:19], v[94:95], v[142:143]
	v_pk_fma_f32 v[144:145], v[18:19], v[78:79], v[144:145]
	v_pk_fma_f32 v[16:17], v[108:109], v[148:149], v[140:141] op_sel:[0,1,0] op_sel_hi:[1,1,1]
	v_pk_fma_f32 v[18:19], v[110:111], v[148:149], v[142:143] op_sel:[0,1,0] op_sel_hi:[1,1,1]
	v_pk_mul_f32 v[146:147], v[16:17], v[96:97]
	v_pk_fma_f32 v[146:147], v[18:19], v[98:99], v[146:147]
	s_waitcnt lgkmcnt(6)
	v_pk_mul_f32 v[132:133], v[16:17], v[44:45]
	v_pk_mul_f32 v[134:135], v[16:17], v[64:65]
	v_add_f32_e32 v202, v144, v145
	v_pk_fma_f32 v[132:133], v[18:19], v[46:47], v[132:133]
	v_pk_fma_f32 v[134:135], v[18:19], v[66:67], v[134:135]
	v_add_f32_e32 v203, v146, v147
	v_pk_mul_f32 v[136:137], v[116:117], v[40:41] op_sel_hi:[0,1]
	v_add_f32_e32 v148, v132, v133
	v_cndmask_b32_e64 v208, v200, v201, s[10:11]
	v_add_f32_e32 v149, v134, v135
	v_pk_mul_f32 v[138:139], v[116:117], v[42:43] op_sel_hi:[0,1]
	v_cndmask_b32_e64 v209, v201, v200, s[10:11]
	v_add_f32_dpp v148, v148, v148 quad_perm:[1,0,3,2] row_mask:0xf bank_mask:0xf bound_ctrl:1
	v_add_f32_dpp v149, v149, v149 quad_perm:[1,0,3,2] row_mask:0xf bank_mask:0xf bound_ctrl:1
	v_cndmask_b32_e64 v210, v202, v203, s[10:11]
	v_pk_fma_f32 v[136:137], v[16:17], v[32:33], v[136:137]
	v_add_f32_dpp v148, v148, v148 quad_perm:[2,3,0,1] row_mask:0xf bank_mask:0xf bound_ctrl:1
	v_cndmask_b32_e64 v211, v203, v202, s[10:11]
	v_add_f32_dpp v149, v149, v149 quad_perm:[2,3,0,1] row_mask:0xf bank_mask:0xf bound_ctrl:1
	v_pk_fma_f32 v[138:139], v[18:19], v[34:35], v[138:139]
	v_add_f32_dpp v212, v209, v208 quad_perm:[1,0,3,2] row_mask:0xf bank_mask:0xf bound_ctrl:1
	v_add_f32_dpp v148, v148, v148 row_half_mirror row_mask:0xf bank_mask:0xf bound_ctrl:1
	v_add_f32_dpp v149, v149, v149 row_half_mirror row_mask:0xf bank_mask:0xf bound_ctrl:1
	v_add_f32_dpp v213, v211, v210 quad_perm:[1,0,3,2] row_mask:0xf bank_mask:0xf bound_ctrl:1
	ds_read_b128 v[84:87], v29 offset:7728
	ds_read_b128 v[104:107], v29 offset:9008
	ds_read_b128 v[80:83], v29 offset:7712
	ds_read_b128 v[72:75], v29 offset:7680
	ds_read_b128 v[88:91], v29 offset:7744
	ds_read_b128 v[100:103], v29 offset:8992
	ds_read_b128 v[92:95], v29 offset:8960
	ds_read_b128 v[76:79], v29 offset:7696
	ds_read_b128 v[108:111], v29 offset:9024
	ds_read_b128 v[96:99], v29 offset:8976
	s_waitcnt lgkmcnt(10)
	v_pk_mul_f32 v[140:141], v[116:117], v[60:61] op_sel:[1,0] op_sel_hi:[1,1]
	v_cndmask_b32_e64 v214, v212, v213, s[14:15]
	v_add_f32_dpp v148, v148, v148 row_mirror row_mask:0xf bank_mask:0xf bound_ctrl:1
	v_add_f32_dpp v149, v149, v149 row_mirror row_mask:0xf bank_mask:0xf bound_ctrl:1
	v_cndmask_b32_e64 v215, v213, v212, s[14:15]
	v_pk_mul_f32 v[142:143], v[116:117], v[62:63] op_sel:[1,0] op_sel_hi:[1,1]
	v_fmac_f32_e32 v149, v116, v122
	v_add_f32_dpp v216, v215, v214 quad_perm:[2,3,0,1] row_mask:0xf bank_mask:0xf bound_ctrl:1
	v_pk_fma_f32 v[16:17], v[48:49], v[148:149], v[136:137] op_sel_hi:[1,0,1]
	v_pk_fma_f32 v[18:19], v[50:51], v[148:149], v[138:139] op_sel_hi:[1,0,1]
	v_add_f32_dpp v216, v216, v216 row_ror:8 row_mask:0xf bank_mask:0xf bound_ctrl:1
	v_pk_fma_f32 v[140:141], v[16:17], v[52:53], v[140:141]
	v_pk_mul_f32 v[144:145], v[16:17], v[36:37]
	v_add_f32_dpp v216, v216, v216 row_ror:4 row_mask:0xf bank_mask:0xf bound_ctrl:1
	v_pk_fma_f32 v[142:143], v[18:19], v[54:55], v[142:143]
	v_pk_fma_f32 v[144:145], v[18:19], v[38:39], v[144:145]
	v_cndmask_b32_e64 v28, v28, v216, s[34:35]
	v_pk_fma_f32 v[16:17], v[68:69], v[148:149], v[140:141] op_sel:[0,1,0] op_sel_hi:[1,1,1]
	v_pk_fma_f32 v[18:19], v[70:71], v[148:149], v[142:143] op_sel:[0,1,0] op_sel_hi:[1,1,1]
	v_pk_mul_f32 v[146:147], v[16:17], v[56:57]
	v_pk_fma_f32 v[146:147], v[18:19], v[58:59], v[146:147]
	s_waitcnt lgkmcnt(6)
	v_pk_mul_f32 v[132:133], v[16:17], v[84:85]
	v_pk_mul_f32 v[134:135], v[16:17], v[104:105]
	v_add_f32_e32 v204, v144, v145
	v_pk_fma_f32 v[132:133], v[18:19], v[86:87], v[132:133]
	v_pk_fma_f32 v[134:135], v[18:19], v[106:107], v[134:135]
	v_add_f32_e32 v205, v146, v147
	v_pk_mul_f32 v[136:137], v[118:119], v[80:81] op_sel_hi:[0,1]
	v_add_f32_e32 v148, v132, v133
	v_add_f32_e32 v149, v134, v135
	v_pk_mul_f32 v[138:139], v[118:119], v[82:83] op_sel_hi:[0,1]
	v_add_f32_dpp v148, v148, v148 quad_perm:[1,0,3,2] row_mask:0xf bank_mask:0xf bound_ctrl:1
	v_add_f32_dpp v149, v149, v149 quad_perm:[1,0,3,2] row_mask:0xf bank_mask:0xf bound_ctrl:1
	v_pk_fma_f32 v[136:137], v[16:17], v[72:73], v[136:137]
	v_add_f32_dpp v148, v148, v148 quad_perm:[2,3,0,1] row_mask:0xf bank_mask:0xf bound_ctrl:1
	v_add_f32_dpp v149, v149, v149 quad_perm:[2,3,0,1] row_mask:0xf bank_mask:0xf bound_ctrl:1
	v_pk_fma_f32 v[138:139], v[18:19], v[74:75], v[138:139]
	v_add_f32_dpp v148, v148, v148 row_half_mirror row_mask:0xf bank_mask:0xf bound_ctrl:1
	v_add_f32_dpp v149, v149, v149 row_half_mirror row_mask:0xf bank_mask:0xf bound_ctrl:1
	ds_read_b128 v[44:47], v29 offset:10288
	ds_read_b128 v[64:67], v29 offset:11568
	ds_read_b128 v[40:43], v29 offset:10272
	ds_read_b128 v[112:115], v31 offset:32
	ds_read_b128 v[32:35], v29 offset:10240
	ds_read_b128 v[124:127], v30 offset:2320
	ds_read_b128 v[48:51], v29 offset:10304
	ds_read_b128 v[60:63], v29 offset:11552
	ds_read_b128 v[52:55], v29 offset:11520
	ds_read_b128 v[36:39], v29 offset:10256
	ds_read_b128 v[68:71], v29 offset:11584
	ds_read_b128 v[56:59], v29 offset:11536
	s_waitcnt lgkmcnt(12)
	v_pk_mul_f32 v[140:141], v[118:119], v[100:101] op_sel:[1,0] op_sel_hi:[1,1]
	v_add_f32_dpp v148, v148, v148 row_mirror row_mask:0xf bank_mask:0xf bound_ctrl:1
	v_add_f32_dpp v149, v149, v149 row_mirror row_mask:0xf bank_mask:0xf bound_ctrl:1
	v_pk_mul_f32 v[142:143], v[118:119], v[102:103] op_sel:[1,0] op_sel_hi:[1,1]
	v_fmac_f32_e32 v149, v118, v123
	v_pk_fma_f32 v[16:17], v[88:89], v[148:149], v[136:137] op_sel_hi:[1,0,1]
	v_pk_fma_f32 v[18:19], v[90:91], v[148:149], v[138:139] op_sel_hi:[1,0,1]
	v_pk_fma_f32 v[140:141], v[16:17], v[92:93], v[140:141]
	v_pk_mul_f32 v[144:145], v[16:17], v[76:77]
	v_pk_fma_f32 v[142:143], v[18:19], v[94:95], v[142:143]
	v_pk_fma_f32 v[144:145], v[18:19], v[78:79], v[144:145]
	v_pk_fma_f32 v[16:17], v[108:109], v[148:149], v[140:141] op_sel:[0,1,0] op_sel_hi:[1,1,1]
	v_pk_fma_f32 v[18:19], v[110:111], v[148:149], v[142:143] op_sel:[0,1,0] op_sel_hi:[1,1,1]
	v_pk_mul_f32 v[146:147], v[16:17], v[96:97]
	v_pk_fma_f32 v[146:147], v[18:19], v[98:99], v[146:147]
	s_waitcnt lgkmcnt(7)
	v_pk_mul_f32 v[132:133], v[16:17], v[44:45]
	v_pk_mul_f32 v[134:135], v[16:17], v[64:65]
	v_add_f32_e32 v206, v144, v145
	v_pk_fma_f32 v[132:133], v[18:19], v[46:47], v[132:133]
	v_pk_fma_f32 v[134:135], v[18:19], v[66:67], v[134:135]
	v_add_f32_e32 v207, v146, v147
	v_pk_mul_f32 v[136:137], v[112:113], v[40:41] op_sel_hi:[0,1]
	v_add_f32_e32 v148, v132, v133
	v_cndmask_b32_e64 v208, v204, v205, s[10:11]
	v_add_f32_e32 v149, v134, v135
	v_pk_mul_f32 v[138:139], v[112:113], v[42:43] op_sel_hi:[0,1]
	v_cndmask_b32_e64 v209, v205, v204, s[10:11]
	v_add_f32_dpp v148, v148, v148 quad_perm:[1,0,3,2] row_mask:0xf bank_mask:0xf bound_ctrl:1
	v_add_f32_dpp v149, v149, v149 quad_perm:[1,0,3,2] row_mask:0xf bank_mask:0xf bound_ctrl:1
	v_cndmask_b32_e64 v210, v206, v207, s[10:11]
	v_pk_fma_f32 v[136:137], v[16:17], v[32:33], v[136:137]
	v_add_f32_dpp v148, v148, v148 quad_perm:[2,3,0,1] row_mask:0xf bank_mask:0xf bound_ctrl:1
	v_cndmask_b32_e64 v211, v207, v206, s[10:11]
	v_add_f32_dpp v149, v149, v149 quad_perm:[2,3,0,1] row_mask:0xf bank_mask:0xf bound_ctrl:1
	v_pk_fma_f32 v[138:139], v[18:19], v[34:35], v[138:139]
	v_add_f32_dpp v212, v209, v208 quad_perm:[1,0,3,2] row_mask:0xf bank_mask:0xf bound_ctrl:1
	v_add_f32_dpp v148, v148, v148 row_half_mirror row_mask:0xf bank_mask:0xf bound_ctrl:1
	v_add_f32_dpp v149, v149, v149 row_half_mirror row_mask:0xf bank_mask:0xf bound_ctrl:1
	v_add_f32_dpp v213, v211, v210 quad_perm:[1,0,3,2] row_mask:0xf bank_mask:0xf bound_ctrl:1
	ds_read_b128 v[84:87], v29 offset:12848
	ds_read_b128 v[104:107], v29 offset:14128
	ds_read_b128 v[80:83], v29 offset:12832
	ds_read_b128 v[72:75], v29 offset:12800
	ds_read_b128 v[88:91], v29 offset:12864
	ds_read_b128 v[100:103], v29 offset:14112
	ds_read_b128 v[92:95], v29 offset:14080
	ds_read_b128 v[76:79], v29 offset:12816
	ds_read_b128 v[108:111], v29 offset:14144
	ds_read_b128 v[96:99], v29 offset:14096
	s_waitcnt lgkmcnt(10)
	v_pk_mul_f32 v[140:141], v[112:113], v[60:61] op_sel:[1,0] op_sel_hi:[1,1]
	v_cndmask_b32_e64 v214, v212, v213, s[14:15]
	v_add_f32_dpp v148, v148, v148 row_mirror row_mask:0xf bank_mask:0xf bound_ctrl:1
	v_add_f32_dpp v149, v149, v149 row_mirror row_mask:0xf bank_mask:0xf bound_ctrl:1
	v_cndmask_b32_e64 v215, v213, v212, s[14:15]
	v_pk_mul_f32 v[142:143], v[112:113], v[62:63] op_sel:[1,0] op_sel_hi:[1,1]
	v_fmac_f32_e32 v149, v112, v124
	v_add_f32_dpp v216, v215, v214 quad_perm:[2,3,0,1] row_mask:0xf bank_mask:0xf bound_ctrl:1
	v_pk_fma_f32 v[16:17], v[48:49], v[148:149], v[136:137] op_sel_hi:[1,0,1]
	v_pk_fma_f32 v[18:19], v[50:51], v[148:149], v[138:139] op_sel_hi:[1,0,1]
	v_add_f32_dpp v216, v216, v216 row_ror:8 row_mask:0xf bank_mask:0xf bound_ctrl:1
	v_pk_fma_f32 v[140:141], v[16:17], v[52:53], v[140:141]
	v_pk_mul_f32 v[144:145], v[16:17], v[36:37]
	v_add_f32_dpp v216, v216, v216 row_ror:4 row_mask:0xf bank_mask:0xf bound_ctrl:1
	v_pk_fma_f32 v[142:143], v[18:19], v[54:55], v[142:143]
	v_pk_fma_f32 v[144:145], v[18:19], v[38:39], v[144:145]
	v_cndmask_b32_e64 v28, v28, v216, s[36:37]
	v_pk_fma_f32 v[16:17], v[68:69], v[148:149], v[140:141] op_sel:[0,1,0] op_sel_hi:[1,1,1]
	v_pk_fma_f32 v[18:19], v[70:71], v[148:149], v[142:143] op_sel:[0,1,0] op_sel_hi:[1,1,1]
	v_pk_mul_f32 v[146:147], v[16:17], v[56:57]
	v_pk_fma_f32 v[146:147], v[18:19], v[58:59], v[146:147]
	s_waitcnt lgkmcnt(6)
	v_pk_mul_f32 v[132:133], v[16:17], v[84:85]
	v_pk_mul_f32 v[134:135], v[16:17], v[104:105]
	v_add_f32_e32 v200, v144, v145
	v_pk_fma_f32 v[132:133], v[18:19], v[86:87], v[132:133]
	v_pk_fma_f32 v[134:135], v[18:19], v[106:107], v[134:135]
	v_add_f32_e32 v201, v146, v147
	v_pk_mul_f32 v[136:137], v[114:115], v[80:81] op_sel_hi:[0,1]
	v_add_f32_e32 v148, v132, v133
	v_add_f32_e32 v149, v134, v135
	v_pk_mul_f32 v[138:139], v[114:115], v[82:83] op_sel_hi:[0,1]
	v_add_f32_dpp v148, v148, v148 quad_perm:[1,0,3,2] row_mask:0xf bank_mask:0xf bound_ctrl:1
	v_add_f32_dpp v149, v149, v149 quad_perm:[1,0,3,2] row_mask:0xf bank_mask:0xf bound_ctrl:1
	v_pk_fma_f32 v[136:137], v[16:17], v[72:73], v[136:137]
	v_add_f32_dpp v148, v148, v148 quad_perm:[2,3,0,1] row_mask:0xf bank_mask:0xf bound_ctrl:1
	v_add_f32_dpp v149, v149, v149 quad_perm:[2,3,0,1] row_mask:0xf bank_mask:0xf bound_ctrl:1
	v_pk_fma_f32 v[138:139], v[18:19], v[74:75], v[138:139]
	v_add_f32_dpp v148, v148, v148 row_half_mirror row_mask:0xf bank_mask:0xf bound_ctrl:1
	v_add_f32_dpp v149, v149, v149 row_half_mirror row_mask:0xf bank_mask:0xf bound_ctrl:1
	ds_read_b128 v[44:47], v29 offset:15408
	ds_read_b128 v[64:67], v29 offset:16688
	ds_read_b128 v[40:43], v29 offset:15392
	ds_read_b128 v[116:119], v31 offset:48
	ds_read_b128 v[32:35], v29 offset:15360
	ds_read_b128 v[48:51], v29 offset:15424
	ds_read_b128 v[60:63], v29 offset:16672
	ds_read_b128 v[52:55], v29 offset:16640
	ds_read_b128 v[36:39], v29 offset:15376
	ds_read_b128 v[68:71], v29 offset:16704
	ds_read_b128 v[56:59], v29 offset:16656
	s_waitcnt lgkmcnt(11)
	v_pk_mul_f32 v[140:141], v[114:115], v[100:101] op_sel:[1,0] op_sel_hi:[1,1]
	v_add_f32_dpp v148, v148, v148 row_mirror row_mask:0xf bank_mask:0xf bound_ctrl:1
	v_add_f32_dpp v149, v149, v149 row_mirror row_mask:0xf bank_mask:0xf bound_ctrl:1
	v_pk_mul_f32 v[142:143], v[114:115], v[102:103] op_sel:[1,0] op_sel_hi:[1,1]
	v_fmac_f32_e32 v149, v114, v125
	v_pk_fma_f32 v[16:17], v[88:89], v[148:149], v[136:137] op_sel_hi:[1,0,1]
	v_pk_fma_f32 v[18:19], v[90:91], v[148:149], v[138:139] op_sel_hi:[1,0,1]
	v_pk_fma_f32 v[140:141], v[16:17], v[92:93], v[140:141]
	v_pk_mul_f32 v[144:145], v[16:17], v[76:77]
	v_pk_fma_f32 v[142:143], v[18:19], v[94:95], v[142:143]
	v_pk_fma_f32 v[144:145], v[18:19], v[78:79], v[144:145]
	v_pk_fma_f32 v[16:17], v[108:109], v[148:149], v[140:141] op_sel:[0,1,0] op_sel_hi:[1,1,1]
	v_pk_fma_f32 v[18:19], v[110:111], v[148:149], v[142:143] op_sel:[0,1,0] op_sel_hi:[1,1,1]
	v_pk_mul_f32 v[146:147], v[16:17], v[96:97]
	v_pk_fma_f32 v[146:147], v[18:19], v[98:99], v[146:147]
	s_waitcnt lgkmcnt(6)
	v_pk_mul_f32 v[132:133], v[16:17], v[44:45]
	v_pk_mul_f32 v[134:135], v[16:17], v[64:65]
	v_add_f32_e32 v202, v144, v145
	v_pk_fma_f32 v[132:133], v[18:19], v[46:47], v[132:133]
	v_pk_fma_f32 v[134:135], v[18:19], v[66:67], v[134:135]
	v_add_f32_e32 v203, v146, v147
	v_pk_mul_f32 v[136:137], v[116:117], v[40:41] op_sel_hi:[0,1]
	v_add_f32_e32 v148, v132, v133
	v_cndmask_b32_e64 v208, v200, v201, s[10:11]
	v_add_f32_e32 v149, v134, v135
	v_pk_mul_f32 v[138:139], v[116:117], v[42:43] op_sel_hi:[0,1]
	v_cndmask_b32_e64 v209, v201, v200, s[10:11]
	v_add_f32_dpp v148, v148, v148 quad_perm:[1,0,3,2] row_mask:0xf bank_mask:0xf bound_ctrl:1
	v_add_f32_dpp v149, v149, v149 quad_perm:[1,0,3,2] row_mask:0xf bank_mask:0xf bound_ctrl:1
	v_cndmask_b32_e64 v210, v202, v203, s[10:11]
	v_pk_fma_f32 v[136:137], v[16:17], v[32:33], v[136:137]
	v_add_f32_dpp v148, v148, v148 quad_perm:[2,3,0,1] row_mask:0xf bank_mask:0xf bound_ctrl:1
	v_cndmask_b32_e64 v211, v203, v202, s[10:11]
	v_add_f32_dpp v149, v149, v149 quad_perm:[2,3,0,1] row_mask:0xf bank_mask:0xf bound_ctrl:1
	v_pk_fma_f32 v[138:139], v[18:19], v[34:35], v[138:139]
	v_add_f32_dpp v212, v209, v208 quad_perm:[1,0,3,2] row_mask:0xf bank_mask:0xf bound_ctrl:1
	v_add_f32_dpp v148, v148, v148 row_half_mirror row_mask:0xf bank_mask:0xf bound_ctrl:1
	v_add_f32_dpp v149, v149, v149 row_half_mirror row_mask:0xf bank_mask:0xf bound_ctrl:1
	v_add_f32_dpp v213, v211, v210 quad_perm:[1,0,3,2] row_mask:0xf bank_mask:0xf bound_ctrl:1
	ds_read_b128 v[84:87], v29 offset:17968
	ds_read_b128 v[104:107], v29 offset:19248
	ds_read_b128 v[80:83], v29 offset:17952
	ds_read_b128 v[72:75], v29 offset:17920
	ds_read_b128 v[88:91], v29 offset:17984
	ds_read_b128 v[100:103], v29 offset:19232
	ds_read_b128 v[92:95], v29 offset:19200
	ds_read_b128 v[76:79], v29 offset:17936
	ds_read_b128 v[108:111], v29 offset:19264
	ds_read_b128 v[96:99], v29 offset:19216
	s_waitcnt lgkmcnt(10)
	v_pk_mul_f32 v[140:141], v[116:117], v[60:61] op_sel:[1,0] op_sel_hi:[1,1]
	v_cndmask_b32_e64 v214, v212, v213, s[14:15]
	v_add_f32_dpp v148, v148, v148 row_mirror row_mask:0xf bank_mask:0xf bound_ctrl:1
	v_add_f32_dpp v149, v149, v149 row_mirror row_mask:0xf bank_mask:0xf bound_ctrl:1
	v_cndmask_b32_e64 v215, v213, v212, s[14:15]
	v_pk_mul_f32 v[142:143], v[116:117], v[62:63] op_sel:[1,0] op_sel_hi:[1,1]
	v_fmac_f32_e32 v149, v116, v126
	v_add_f32_dpp v216, v215, v214 quad_perm:[2,3,0,1] row_mask:0xf bank_mask:0xf bound_ctrl:1
	v_pk_fma_f32 v[16:17], v[48:49], v[148:149], v[136:137] op_sel_hi:[1,0,1]
	v_pk_fma_f32 v[18:19], v[50:51], v[148:149], v[138:139] op_sel_hi:[1,0,1]
	v_add_f32_dpp v216, v216, v216 row_ror:8 row_mask:0xf bank_mask:0xf bound_ctrl:1
	v_pk_fma_f32 v[140:141], v[16:17], v[52:53], v[140:141]
	v_pk_mul_f32 v[144:145], v[16:17], v[36:37]
	v_add_f32_dpp v216, v216, v216 row_ror:4 row_mask:0xf bank_mask:0xf bound_ctrl:1
	v_pk_fma_f32 v[142:143], v[18:19], v[54:55], v[142:143]
	v_pk_fma_f32 v[144:145], v[18:19], v[38:39], v[144:145]
	v_cndmask_b32_e64 v28, v28, v216, s[42:43]
	v_pk_fma_f32 v[16:17], v[68:69], v[148:149], v[140:141] op_sel:[0,1,0] op_sel_hi:[1,1,1]
	v_pk_fma_f32 v[18:19], v[70:71], v[148:149], v[142:143] op_sel:[0,1,0] op_sel_hi:[1,1,1]
	v_pk_mul_f32 v[146:147], v[16:17], v[56:57]
	v_pk_fma_f32 v[146:147], v[18:19], v[58:59], v[146:147]
	s_waitcnt lgkmcnt(6)
	v_pk_mul_f32 v[132:133], v[16:17], v[84:85]
	v_pk_mul_f32 v[134:135], v[16:17], v[104:105]
	v_add_f32_e32 v204, v144, v145
	v_pk_fma_f32 v[132:133], v[18:19], v[86:87], v[132:133]
	v_pk_fma_f32 v[134:135], v[18:19], v[106:107], v[134:135]
	v_add_f32_e32 v205, v146, v147
	v_pk_mul_f32 v[136:137], v[118:119], v[80:81] op_sel_hi:[0,1]
	v_add_f32_e32 v148, v132, v133
	v_add_f32_e32 v149, v134, v135
	v_pk_mul_f32 v[138:139], v[118:119], v[82:83] op_sel_hi:[0,1]
	v_add_f32_dpp v148, v148, v148 quad_perm:[1,0,3,2] row_mask:0xf bank_mask:0xf bound_ctrl:1
	v_add_f32_dpp v149, v149, v149 quad_perm:[1,0,3,2] row_mask:0xf bank_mask:0xf bound_ctrl:1
	v_pk_fma_f32 v[136:137], v[16:17], v[72:73], v[136:137]
	v_add_f32_dpp v148, v148, v148 quad_perm:[2,3,0,1] row_mask:0xf bank_mask:0xf bound_ctrl:1
	v_add_f32_dpp v149, v149, v149 quad_perm:[2,3,0,1] row_mask:0xf bank_mask:0xf bound_ctrl:1
	v_pk_fma_f32 v[138:139], v[18:19], v[74:75], v[138:139]
	v_add_f32_dpp v148, v148, v148 row_half_mirror row_mask:0xf bank_mask:0xf bound_ctrl:1
	v_add_f32_dpp v149, v149, v149 row_half_mirror row_mask:0xf bank_mask:0xf bound_ctrl:1
	ds_read_b128 v[44:47], v29 offset:20528
	ds_read_b128 v[64:67], v29 offset:21808
	ds_read_b128 v[40:43], v29 offset:20512
	ds_read_b128 v[112:115], v31 offset:64
	ds_read_b128 v[32:35], v29 offset:20480
	ds_read_b128 v[120:123], v30 offset:2336
	ds_read_b128 v[48:51], v29 offset:20544
	ds_read_b128 v[60:63], v29 offset:21792
	ds_read_b128 v[52:55], v29 offset:21760
	ds_read_b128 v[36:39], v29 offset:20496
	ds_read_b128 v[68:71], v29 offset:21824
	ds_read_b128 v[56:59], v29 offset:21776
	s_waitcnt lgkmcnt(12)
	v_pk_mul_f32 v[140:141], v[118:119], v[100:101] op_sel:[1,0] op_sel_hi:[1,1]
	v_add_f32_dpp v148, v148, v148 row_mirror row_mask:0xf bank_mask:0xf bound_ctrl:1
	v_add_f32_dpp v149, v149, v149 row_mirror row_mask:0xf bank_mask:0xf bound_ctrl:1
	v_pk_mul_f32 v[142:143], v[118:119], v[102:103] op_sel:[1,0] op_sel_hi:[1,1]
	v_fmac_f32_e32 v149, v118, v127
	v_pk_fma_f32 v[16:17], v[88:89], v[148:149], v[136:137] op_sel_hi:[1,0,1]
	v_pk_fma_f32 v[18:19], v[90:91], v[148:149], v[138:139] op_sel_hi:[1,0,1]
	v_pk_fma_f32 v[140:141], v[16:17], v[92:93], v[140:141]
	v_pk_mul_f32 v[144:145], v[16:17], v[76:77]
	v_pk_fma_f32 v[142:143], v[18:19], v[94:95], v[142:143]
	v_pk_fma_f32 v[144:145], v[18:19], v[78:79], v[144:145]
	v_pk_fma_f32 v[16:17], v[108:109], v[148:149], v[140:141] op_sel:[0,1,0] op_sel_hi:[1,1,1]
	v_pk_fma_f32 v[18:19], v[110:111], v[148:149], v[142:143] op_sel:[0,1,0] op_sel_hi:[1,1,1]
	v_pk_mul_f32 v[146:147], v[16:17], v[96:97]
	v_pk_fma_f32 v[146:147], v[18:19], v[98:99], v[146:147]
	s_waitcnt lgkmcnt(7)
	v_pk_mul_f32 v[132:133], v[16:17], v[44:45]
	v_pk_mul_f32 v[134:135], v[16:17], v[64:65]
	v_add_f32_e32 v206, v144, v145
	v_pk_fma_f32 v[132:133], v[18:19], v[46:47], v[132:133]
	v_pk_fma_f32 v[134:135], v[18:19], v[66:67], v[134:135]
	v_add_f32_e32 v207, v146, v147
	v_pk_mul_f32 v[136:137], v[112:113], v[40:41] op_sel_hi:[0,1]
	v_add_f32_e32 v148, v132, v133
	v_cndmask_b32_e64 v208, v204, v205, s[10:11]
	v_add_f32_e32 v149, v134, v135
	v_pk_mul_f32 v[138:139], v[112:113], v[42:43] op_sel_hi:[0,1]
	v_cndmask_b32_e64 v209, v205, v204, s[10:11]
	v_add_f32_dpp v148, v148, v148 quad_perm:[1,0,3,2] row_mask:0xf bank_mask:0xf bound_ctrl:1
	v_add_f32_dpp v149, v149, v149 quad_perm:[1,0,3,2] row_mask:0xf bank_mask:0xf bound_ctrl:1
	v_cndmask_b32_e64 v210, v206, v207, s[10:11]
	v_pk_fma_f32 v[136:137], v[16:17], v[32:33], v[136:137]
	v_add_f32_dpp v148, v148, v148 quad_perm:[2,3,0,1] row_mask:0xf bank_mask:0xf bound_ctrl:1
	v_cndmask_b32_e64 v211, v207, v206, s[10:11]
	v_add_f32_dpp v149, v149, v149 quad_perm:[2,3,0,1] row_mask:0xf bank_mask:0xf bound_ctrl:1
	v_pk_fma_f32 v[138:139], v[18:19], v[34:35], v[138:139]
	v_add_f32_dpp v212, v209, v208 quad_perm:[1,0,3,2] row_mask:0xf bank_mask:0xf bound_ctrl:1
	v_add_f32_dpp v148, v148, v148 row_half_mirror row_mask:0xf bank_mask:0xf bound_ctrl:1
	v_add_f32_dpp v149, v149, v149 row_half_mirror row_mask:0xf bank_mask:0xf bound_ctrl:1
	v_add_f32_dpp v213, v211, v210 quad_perm:[1,0,3,2] row_mask:0xf bank_mask:0xf bound_ctrl:1
	ds_read_b128 v[84:87], v29 offset:23088
	ds_read_b128 v[104:107], v29 offset:24368
	ds_read_b128 v[80:83], v29 offset:23072
	ds_read_b128 v[72:75], v29 offset:23040
	ds_read_b128 v[88:91], v29 offset:23104
	ds_read_b128 v[100:103], v29 offset:24352
	ds_read_b128 v[92:95], v29 offset:24320
	ds_read_b128 v[76:79], v29 offset:23056
	ds_read_b128 v[108:111], v29 offset:24384
	ds_read_b128 v[96:99], v29 offset:24336
	s_waitcnt lgkmcnt(10)
	v_pk_mul_f32 v[140:141], v[112:113], v[60:61] op_sel:[1,0] op_sel_hi:[1,1]
	v_cndmask_b32_e64 v214, v212, v213, s[14:15]
	v_add_f32_dpp v148, v148, v148 row_mirror row_mask:0xf bank_mask:0xf bound_ctrl:1
	v_add_f32_dpp v149, v149, v149 row_mirror row_mask:0xf bank_mask:0xf bound_ctrl:1
	v_cndmask_b32_e64 v215, v213, v212, s[14:15]
	v_pk_mul_f32 v[142:143], v[112:113], v[62:63] op_sel:[1,0] op_sel_hi:[1,1]
	v_fmac_f32_e32 v149, v112, v120
	v_add_f32_dpp v216, v215, v214 quad_perm:[2,3,0,1] row_mask:0xf bank_mask:0xf bound_ctrl:1
	v_pk_fma_f32 v[16:17], v[48:49], v[148:149], v[136:137] op_sel_hi:[1,0,1]
	v_pk_fma_f32 v[18:19], v[50:51], v[148:149], v[138:139] op_sel_hi:[1,0,1]
	v_add_f32_dpp v216, v216, v216 row_ror:8 row_mask:0xf bank_mask:0xf bound_ctrl:1
	v_pk_fma_f32 v[140:141], v[16:17], v[52:53], v[140:141]
	v_pk_mul_f32 v[144:145], v[16:17], v[36:37]
	v_add_f32_dpp v216, v216, v216 row_ror:4 row_mask:0xf bank_mask:0xf bound_ctrl:1
	v_pk_fma_f32 v[142:143], v[18:19], v[54:55], v[142:143]
	v_pk_fma_f32 v[144:145], v[18:19], v[38:39], v[144:145]
	v_cndmask_b32_e64 v28, v28, v216, s[44:45]
	v_pk_fma_f32 v[16:17], v[68:69], v[148:149], v[140:141] op_sel:[0,1,0] op_sel_hi:[1,1,1]
	v_pk_fma_f32 v[18:19], v[70:71], v[148:149], v[142:143] op_sel:[0,1,0] op_sel_hi:[1,1,1]
	v_add_co_u32_e32 v218, vcc, s59, v12
	v_pk_mul_f32 v[146:147], v[16:17], v[56:57]
	v_pk_fma_f32 v[146:147], v[18:19], v[58:59], v[146:147]
	s_nop 1
	v_addc_co_u32_e32 v219, vcc, 0, v13, vcc
	global_store_dword v[218:219], v28, off
	s_waitcnt lgkmcnt(6)
	v_pk_mul_f32 v[132:133], v[16:17], v[84:85]
	v_pk_mul_f32 v[134:135], v[16:17], v[104:105]
	v_add_f32_e32 v200, v144, v145
	v_pk_fma_f32 v[132:133], v[18:19], v[86:87], v[132:133]
	v_pk_fma_f32 v[134:135], v[18:19], v[106:107], v[134:135]
	v_add_f32_e32 v201, v146, v147
	v_pk_mul_f32 v[136:137], v[114:115], v[80:81] op_sel_hi:[0,1]
	v_add_f32_e32 v148, v132, v133
	v_add_f32_e32 v149, v134, v135
	v_pk_mul_f32 v[138:139], v[114:115], v[82:83] op_sel_hi:[0,1]
	v_add_f32_dpp v148, v148, v148 quad_perm:[1,0,3,2] row_mask:0xf bank_mask:0xf bound_ctrl:1
	v_add_f32_dpp v149, v149, v149 quad_perm:[1,0,3,2] row_mask:0xf bank_mask:0xf bound_ctrl:1
	v_pk_fma_f32 v[136:137], v[16:17], v[72:73], v[136:137]
	v_add_f32_dpp v148, v148, v148 quad_perm:[2,3,0,1] row_mask:0xf bank_mask:0xf bound_ctrl:1
	v_add_f32_dpp v149, v149, v149 quad_perm:[2,3,0,1] row_mask:0xf bank_mask:0xf bound_ctrl:1
	v_pk_fma_f32 v[138:139], v[18:19], v[74:75], v[138:139]
	v_add_f32_dpp v148, v148, v148 row_half_mirror row_mask:0xf bank_mask:0xf bound_ctrl:1
	v_add_f32_dpp v149, v149, v149 row_half_mirror row_mask:0xf bank_mask:0xf bound_ctrl:1
	ds_read_b128 v[44:47], v29 offset:25648
	ds_read_b128 v[64:67], v29 offset:26928
	ds_read_b128 v[40:43], v29 offset:25632
	ds_read_b128 v[116:119], v31 offset:80
	ds_read_b128 v[32:35], v29 offset:25600
	ds_read_b128 v[48:51], v29 offset:25664
	ds_read_b128 v[60:63], v29 offset:26912
	ds_read_b128 v[52:55], v29 offset:26880
	ds_read_b128 v[36:39], v29 offset:25616
	ds_read_b128 v[68:71], v29 offset:26944
	ds_read_b128 v[56:59], v29 offset:26896
	s_waitcnt lgkmcnt(11)
	v_pk_mul_f32 v[140:141], v[114:115], v[100:101] op_sel:[1,0] op_sel_hi:[1,1]
	v_add_f32_dpp v148, v148, v148 row_mirror row_mask:0xf bank_mask:0xf bound_ctrl:1
	v_add_f32_dpp v149, v149, v149 row_mirror row_mask:0xf bank_mask:0xf bound_ctrl:1
	v_pk_mul_f32 v[142:143], v[114:115], v[102:103] op_sel:[1,0] op_sel_hi:[1,1]
	v_fmac_f32_e32 v149, v114, v121
	v_pk_fma_f32 v[16:17], v[88:89], v[148:149], v[136:137] op_sel_hi:[1,0,1]
	v_pk_fma_f32 v[18:19], v[90:91], v[148:149], v[138:139] op_sel_hi:[1,0,1]
	v_pk_fma_f32 v[140:141], v[16:17], v[92:93], v[140:141]
	v_pk_mul_f32 v[144:145], v[16:17], v[76:77]
	v_pk_fma_f32 v[142:143], v[18:19], v[94:95], v[142:143]
	v_pk_fma_f32 v[144:145], v[18:19], v[78:79], v[144:145]
	v_pk_fma_f32 v[16:17], v[108:109], v[148:149], v[140:141] op_sel:[0,1,0] op_sel_hi:[1,1,1]
	v_pk_fma_f32 v[18:19], v[110:111], v[148:149], v[142:143] op_sel:[0,1,0] op_sel_hi:[1,1,1]
	v_pk_mul_f32 v[146:147], v[16:17], v[96:97]
	v_pk_fma_f32 v[146:147], v[18:19], v[98:99], v[146:147]
	s_waitcnt lgkmcnt(6)
	v_pk_mul_f32 v[132:133], v[16:17], v[44:45]
	v_pk_mul_f32 v[134:135], v[16:17], v[64:65]
	v_add_f32_e32 v202, v144, v145
	v_pk_fma_f32 v[132:133], v[18:19], v[46:47], v[132:133]
	v_pk_fma_f32 v[134:135], v[18:19], v[66:67], v[134:135]
	v_add_f32_e32 v203, v146, v147
	v_pk_mul_f32 v[136:137], v[116:117], v[40:41] op_sel_hi:[0,1]
	v_add_f32_e32 v148, v132, v133
	v_cndmask_b32_e64 v208, v200, v201, s[10:11]
	v_add_f32_e32 v149, v134, v135
	v_pk_mul_f32 v[138:139], v[116:117], v[42:43] op_sel_hi:[0,1]
	v_cndmask_b32_e64 v209, v201, v200, s[10:11]
	v_add_f32_dpp v148, v148, v148 quad_perm:[1,0,3,2] row_mask:0xf bank_mask:0xf bound_ctrl:1
	v_add_f32_dpp v149, v149, v149 quad_perm:[1,0,3,2] row_mask:0xf bank_mask:0xf bound_ctrl:1
	v_cndmask_b32_e64 v210, v202, v203, s[10:11]
	v_pk_fma_f32 v[136:137], v[16:17], v[32:33], v[136:137]
	v_add_f32_dpp v148, v148, v148 quad_perm:[2,3,0,1] row_mask:0xf bank_mask:0xf bound_ctrl:1
	v_cndmask_b32_e64 v211, v203, v202, s[10:11]
	v_add_f32_dpp v149, v149, v149 quad_perm:[2,3,0,1] row_mask:0xf bank_mask:0xf bound_ctrl:1
	v_pk_fma_f32 v[138:139], v[18:19], v[34:35], v[138:139]
	v_add_f32_dpp v212, v209, v208 quad_perm:[1,0,3,2] row_mask:0xf bank_mask:0xf bound_ctrl:1
	v_add_f32_dpp v148, v148, v148 row_half_mirror row_mask:0xf bank_mask:0xf bound_ctrl:1
	v_add_f32_dpp v149, v149, v149 row_half_mirror row_mask:0xf bank_mask:0xf bound_ctrl:1
	v_add_f32_dpp v213, v211, v210 quad_perm:[1,0,3,2] row_mask:0xf bank_mask:0xf bound_ctrl:1
	ds_read_b128 v[84:87], v29 offset:28208
	ds_read_b128 v[104:107], v29 offset:29488
	ds_read_b128 v[80:83], v29 offset:28192
	ds_read_b128 v[72:75], v29 offset:28160
	ds_read_b128 v[88:91], v29 offset:28224
	ds_read_b128 v[100:103], v29 offset:29472
	ds_read_b128 v[92:95], v29 offset:29440
	ds_read_b128 v[76:79], v29 offset:28176
	ds_read_b128 v[108:111], v29 offset:29504
	ds_read_b128 v[96:99], v29 offset:29456
	s_waitcnt lgkmcnt(10)
	v_pk_mul_f32 v[140:141], v[116:117], v[60:61] op_sel:[1,0] op_sel_hi:[1,1]
	v_cndmask_b32_e64 v214, v212, v213, s[14:15]
	v_add_f32_dpp v148, v148, v148 row_mirror row_mask:0xf bank_mask:0xf bound_ctrl:1
	v_add_f32_dpp v149, v149, v149 row_mirror row_mask:0xf bank_mask:0xf bound_ctrl:1
	v_cndmask_b32_e64 v215, v213, v212, s[14:15]
	v_pk_mul_f32 v[142:143], v[116:117], v[62:63] op_sel:[1,0] op_sel_hi:[1,1]
	v_fmac_f32_e32 v149, v116, v122
	v_add_f32_dpp v216, v215, v214 quad_perm:[2,3,0,1] row_mask:0xf bank_mask:0xf bound_ctrl:1
	v_pk_fma_f32 v[16:17], v[48:49], v[148:149], v[136:137] op_sel_hi:[1,0,1]
	v_pk_fma_f32 v[18:19], v[50:51], v[148:149], v[138:139] op_sel_hi:[1,0,1]
	v_add_f32_dpp v216, v216, v216 row_ror:8 row_mask:0xf bank_mask:0xf bound_ctrl:1
	v_pk_fma_f32 v[140:141], v[16:17], v[52:53], v[140:141]
	v_pk_mul_f32 v[144:145], v[16:17], v[36:37]
	v_add_f32_dpp v216, v216, v216 row_ror:4 row_mask:0xf bank_mask:0xf bound_ctrl:1
	v_pk_fma_f32 v[142:143], v[18:19], v[54:55], v[142:143]
	v_pk_fma_f32 v[144:145], v[18:19], v[38:39], v[144:145]
	v_cndmask_b32_e64 v28, v28, v216, s[34:35]
	v_pk_fma_f32 v[16:17], v[68:69], v[148:149], v[140:141] op_sel:[0,1,0] op_sel_hi:[1,1,1]
	v_pk_fma_f32 v[18:19], v[70:71], v[148:149], v[142:143] op_sel:[0,1,0] op_sel_hi:[1,1,1]
	v_pk_mul_f32 v[146:147], v[16:17], v[56:57]
	v_pk_fma_f32 v[146:147], v[18:19], v[58:59], v[146:147]
	s_waitcnt lgkmcnt(6)
	v_pk_mul_f32 v[132:133], v[16:17], v[84:85]
	v_pk_mul_f32 v[134:135], v[16:17], v[104:105]
	v_add_f32_e32 v204, v144, v145
	v_pk_fma_f32 v[132:133], v[18:19], v[86:87], v[132:133]
	v_pk_fma_f32 v[134:135], v[18:19], v[106:107], v[134:135]
	v_add_f32_e32 v205, v146, v147
	v_pk_mul_f32 v[136:137], v[118:119], v[80:81] op_sel_hi:[0,1]
	v_add_f32_e32 v148, v132, v133
	v_add_f32_e32 v149, v134, v135
	v_pk_mul_f32 v[138:139], v[118:119], v[82:83] op_sel_hi:[0,1]
	v_add_f32_dpp v148, v148, v148 quad_perm:[1,0,3,2] row_mask:0xf bank_mask:0xf bound_ctrl:1
	v_add_f32_dpp v149, v149, v149 quad_perm:[1,0,3,2] row_mask:0xf bank_mask:0xf bound_ctrl:1
	v_pk_fma_f32 v[136:137], v[16:17], v[72:73], v[136:137]
	v_add_f32_dpp v148, v148, v148 quad_perm:[2,3,0,1] row_mask:0xf bank_mask:0xf bound_ctrl:1
	v_add_f32_dpp v149, v149, v149 quad_perm:[2,3,0,1] row_mask:0xf bank_mask:0xf bound_ctrl:1
	v_pk_fma_f32 v[138:139], v[18:19], v[74:75], v[138:139]
	v_add_f32_dpp v148, v148, v148 row_half_mirror row_mask:0xf bank_mask:0xf bound_ctrl:1
	v_add_f32_dpp v149, v149, v149 row_half_mirror row_mask:0xf bank_mask:0xf bound_ctrl:1
	ds_read_b128 v[44:47], v29 offset:30768
	ds_read_b128 v[64:67], v29 offset:32048
	ds_read_b128 v[40:43], v29 offset:30752
	ds_read_b128 v[112:115], v31 offset:96
	ds_read_b128 v[32:35], v29 offset:30720
	ds_read_b128 v[124:127], v30 offset:2352
	ds_read_b128 v[48:51], v29 offset:30784
	ds_read_b128 v[60:63], v29 offset:32032
	ds_read_b128 v[52:55], v29 offset:32000
	ds_read_b128 v[36:39], v29 offset:30736
	ds_read_b128 v[68:71], v29 offset:32064
	ds_read_b128 v[56:59], v29 offset:32016
	s_waitcnt lgkmcnt(12)
	v_pk_mul_f32 v[140:141], v[118:119], v[100:101] op_sel:[1,0] op_sel_hi:[1,1]
	v_add_f32_dpp v148, v148, v148 row_mirror row_mask:0xf bank_mask:0xf bound_ctrl:1
	v_add_f32_dpp v149, v149, v149 row_mirror row_mask:0xf bank_mask:0xf bound_ctrl:1
	v_pk_mul_f32 v[142:143], v[118:119], v[102:103] op_sel:[1,0] op_sel_hi:[1,1]
	v_fmac_f32_e32 v149, v118, v123
	v_pk_fma_f32 v[16:17], v[88:89], v[148:149], v[136:137] op_sel_hi:[1,0,1]
	v_pk_fma_f32 v[18:19], v[90:91], v[148:149], v[138:139] op_sel_hi:[1,0,1]
	v_pk_fma_f32 v[140:141], v[16:17], v[92:93], v[140:141]
	v_pk_mul_f32 v[144:145], v[16:17], v[76:77]
	v_pk_fma_f32 v[142:143], v[18:19], v[94:95], v[142:143]
	v_pk_fma_f32 v[144:145], v[18:19], v[78:79], v[144:145]
	v_pk_fma_f32 v[16:17], v[108:109], v[148:149], v[140:141] op_sel:[0,1,0] op_sel_hi:[1,1,1]
	v_pk_fma_f32 v[18:19], v[110:111], v[148:149], v[142:143] op_sel:[0,1,0] op_sel_hi:[1,1,1]
	v_pk_mul_f32 v[146:147], v[16:17], v[96:97]
	v_pk_fma_f32 v[146:147], v[18:19], v[98:99], v[146:147]
	s_waitcnt lgkmcnt(7)
	v_pk_mul_f32 v[132:133], v[16:17], v[44:45]
	v_pk_mul_f32 v[134:135], v[16:17], v[64:65]
	v_add_f32_e32 v206, v144, v145
	v_pk_fma_f32 v[132:133], v[18:19], v[46:47], v[132:133]
	v_pk_fma_f32 v[134:135], v[18:19], v[66:67], v[134:135]
	v_add_f32_e32 v207, v146, v147
	v_pk_mul_f32 v[136:137], v[112:113], v[40:41] op_sel_hi:[0,1]
	v_add_f32_e32 v148, v132, v133
	v_cndmask_b32_e64 v208, v204, v205, s[10:11]
	v_add_f32_e32 v149, v134, v135
	v_pk_mul_f32 v[138:139], v[112:113], v[42:43] op_sel_hi:[0,1]
	v_cndmask_b32_e64 v209, v205, v204, s[10:11]
	v_add_f32_dpp v148, v148, v148 quad_perm:[1,0,3,2] row_mask:0xf bank_mask:0xf bound_ctrl:1
	v_add_f32_dpp v149, v149, v149 quad_perm:[1,0,3,2] row_mask:0xf bank_mask:0xf bound_ctrl:1
	v_cndmask_b32_e64 v210, v206, v207, s[10:11]
	v_pk_fma_f32 v[136:137], v[16:17], v[32:33], v[136:137]
	v_add_f32_dpp v148, v148, v148 quad_perm:[2,3,0,1] row_mask:0xf bank_mask:0xf bound_ctrl:1
	v_cndmask_b32_e64 v211, v207, v206, s[10:11]
	v_add_f32_dpp v149, v149, v149 quad_perm:[2,3,0,1] row_mask:0xf bank_mask:0xf bound_ctrl:1
	v_pk_fma_f32 v[138:139], v[18:19], v[34:35], v[138:139]
	v_add_f32_dpp v212, v209, v208 quad_perm:[1,0,3,2] row_mask:0xf bank_mask:0xf bound_ctrl:1
	v_add_f32_dpp v148, v148, v148 row_half_mirror row_mask:0xf bank_mask:0xf bound_ctrl:1
	v_add_f32_dpp v149, v149, v149 row_half_mirror row_mask:0xf bank_mask:0xf bound_ctrl:1
	v_add_f32_dpp v213, v211, v210 quad_perm:[1,0,3,2] row_mask:0xf bank_mask:0xf bound_ctrl:1
	ds_read_b128 v[84:87], v29 offset:33328
	ds_read_b128 v[104:107], v29 offset:34608
	ds_read_b128 v[80:83], v29 offset:33312
	ds_read_b128 v[72:75], v29 offset:33280
	ds_read_b128 v[88:91], v29 offset:33344
	ds_read_b128 v[100:103], v29 offset:34592
	ds_read_b128 v[92:95], v29 offset:34560
	ds_read_b128 v[76:79], v29 offset:33296
	ds_read_b128 v[108:111], v29 offset:34624
	ds_read_b128 v[96:99], v29 offset:34576
	s_waitcnt lgkmcnt(10)
	v_pk_mul_f32 v[140:141], v[112:113], v[60:61] op_sel:[1,0] op_sel_hi:[1,1]
	v_cndmask_b32_e64 v214, v212, v213, s[14:15]
	v_add_f32_dpp v148, v148, v148 row_mirror row_mask:0xf bank_mask:0xf bound_ctrl:1
	v_add_f32_dpp v149, v149, v149 row_mirror row_mask:0xf bank_mask:0xf bound_ctrl:1
	v_cndmask_b32_e64 v215, v213, v212, s[14:15]
	v_pk_mul_f32 v[142:143], v[112:113], v[62:63] op_sel:[1,0] op_sel_hi:[1,1]
	v_fmac_f32_e32 v149, v112, v124
	v_add_f32_dpp v216, v215, v214 quad_perm:[2,3,0,1] row_mask:0xf bank_mask:0xf bound_ctrl:1
	v_pk_fma_f32 v[16:17], v[48:49], v[148:149], v[136:137] op_sel_hi:[1,0,1]
	v_pk_fma_f32 v[18:19], v[50:51], v[148:149], v[138:139] op_sel_hi:[1,0,1]
	v_add_f32_dpp v216, v216, v216 row_ror:8 row_mask:0xf bank_mask:0xf bound_ctrl:1
	v_pk_fma_f32 v[140:141], v[16:17], v[52:53], v[140:141]
	v_pk_mul_f32 v[144:145], v[16:17], v[36:37]
	v_add_f32_dpp v216, v216, v216 row_ror:4 row_mask:0xf bank_mask:0xf bound_ctrl:1
	v_pk_fma_f32 v[142:143], v[18:19], v[54:55], v[142:143]
	v_pk_fma_f32 v[144:145], v[18:19], v[38:39], v[144:145]
	v_cndmask_b32_e64 v28, v28, v216, s[36:37]
	v_pk_fma_f32 v[16:17], v[68:69], v[148:149], v[140:141] op_sel:[0,1,0] op_sel_hi:[1,1,1]
	v_pk_fma_f32 v[18:19], v[70:71], v[148:149], v[142:143] op_sel:[0,1,0] op_sel_hi:[1,1,1]
	v_pk_mul_f32 v[146:147], v[16:17], v[56:57]
	v_pk_fma_f32 v[146:147], v[18:19], v[58:59], v[146:147]
	s_waitcnt lgkmcnt(6)
	v_pk_mul_f32 v[132:133], v[16:17], v[84:85]
	v_pk_mul_f32 v[134:135], v[16:17], v[104:105]
	v_add_f32_e32 v200, v144, v145
	v_pk_fma_f32 v[132:133], v[18:19], v[86:87], v[132:133]
	v_pk_fma_f32 v[134:135], v[18:19], v[106:107], v[134:135]
	v_add_f32_e32 v201, v146, v147
	v_pk_mul_f32 v[136:137], v[114:115], v[80:81] op_sel_hi:[0,1]
	v_add_f32_e32 v148, v132, v133
	v_add_f32_e32 v149, v134, v135
	v_pk_mul_f32 v[138:139], v[114:115], v[82:83] op_sel_hi:[0,1]
	v_add_f32_dpp v148, v148, v148 quad_perm:[1,0,3,2] row_mask:0xf bank_mask:0xf bound_ctrl:1
	v_add_f32_dpp v149, v149, v149 quad_perm:[1,0,3,2] row_mask:0xf bank_mask:0xf bound_ctrl:1
	v_pk_fma_f32 v[136:137], v[16:17], v[72:73], v[136:137]
	v_add_f32_dpp v148, v148, v148 quad_perm:[2,3,0,1] row_mask:0xf bank_mask:0xf bound_ctrl:1
	v_add_f32_dpp v149, v149, v149 quad_perm:[2,3,0,1] row_mask:0xf bank_mask:0xf bound_ctrl:1
	v_pk_fma_f32 v[138:139], v[18:19], v[74:75], v[138:139]
	v_add_f32_dpp v148, v148, v148 row_half_mirror row_mask:0xf bank_mask:0xf bound_ctrl:1
	v_add_f32_dpp v149, v149, v149 row_half_mirror row_mask:0xf bank_mask:0xf bound_ctrl:1
	ds_read_b128 v[44:47], v29 offset:35888
	ds_read_b128 v[64:67], v29 offset:37168
	ds_read_b128 v[40:43], v29 offset:35872
	ds_read_b128 v[116:119], v31 offset:112
	ds_read_b128 v[32:35], v29 offset:35840
	ds_read_b128 v[48:51], v29 offset:35904
	ds_read_b128 v[60:63], v29 offset:37152
	ds_read_b128 v[52:55], v29 offset:37120
	ds_read_b128 v[36:39], v29 offset:35856
	ds_read_b128 v[68:71], v29 offset:37184
	ds_read_b128 v[56:59], v29 offset:37136
	s_waitcnt lgkmcnt(11)
	v_pk_mul_f32 v[140:141], v[114:115], v[100:101] op_sel:[1,0] op_sel_hi:[1,1]
	v_add_f32_dpp v148, v148, v148 row_mirror row_mask:0xf bank_mask:0xf bound_ctrl:1
	v_add_f32_dpp v149, v149, v149 row_mirror row_mask:0xf bank_mask:0xf bound_ctrl:1
	v_pk_mul_f32 v[142:143], v[114:115], v[102:103] op_sel:[1,0] op_sel_hi:[1,1]
	v_fmac_f32_e32 v149, v114, v125
	v_pk_fma_f32 v[16:17], v[88:89], v[148:149], v[136:137] op_sel_hi:[1,0,1]
	v_pk_fma_f32 v[18:19], v[90:91], v[148:149], v[138:139] op_sel_hi:[1,0,1]
	v_pk_fma_f32 v[140:141], v[16:17], v[92:93], v[140:141]
	v_pk_mul_f32 v[144:145], v[16:17], v[76:77]
	v_pk_fma_f32 v[142:143], v[18:19], v[94:95], v[142:143]
	v_pk_fma_f32 v[144:145], v[18:19], v[78:79], v[144:145]
	v_pk_fma_f32 v[16:17], v[108:109], v[148:149], v[140:141] op_sel:[0,1,0] op_sel_hi:[1,1,1]
	v_pk_fma_f32 v[18:19], v[110:111], v[148:149], v[142:143] op_sel:[0,1,0] op_sel_hi:[1,1,1]
	v_pk_mul_f32 v[146:147], v[16:17], v[96:97]
	v_pk_fma_f32 v[146:147], v[18:19], v[98:99], v[146:147]
	s_waitcnt lgkmcnt(6)
	v_pk_mul_f32 v[132:133], v[16:17], v[44:45]
	v_pk_mul_f32 v[134:135], v[16:17], v[64:65]
	v_add_f32_e32 v202, v144, v145
	v_pk_fma_f32 v[132:133], v[18:19], v[46:47], v[132:133]
	v_pk_fma_f32 v[134:135], v[18:19], v[66:67], v[134:135]
	v_add_f32_e32 v203, v146, v147
	v_pk_mul_f32 v[136:137], v[116:117], v[40:41] op_sel_hi:[0,1]
	v_add_f32_e32 v148, v132, v133
	v_cndmask_b32_e64 v208, v200, v201, s[10:11]
	v_add_f32_e32 v149, v134, v135
	v_pk_mul_f32 v[138:139], v[116:117], v[42:43] op_sel_hi:[0,1]
	v_cndmask_b32_e64 v209, v201, v200, s[10:11]
	v_add_f32_dpp v148, v148, v148 quad_perm:[1,0,3,2] row_mask:0xf bank_mask:0xf bound_ctrl:1
	v_add_f32_dpp v149, v149, v149 quad_perm:[1,0,3,2] row_mask:0xf bank_mask:0xf bound_ctrl:1
	v_cndmask_b32_e64 v210, v202, v203, s[10:11]
	v_pk_fma_f32 v[136:137], v[16:17], v[32:33], v[136:137]
	v_add_f32_dpp v148, v148, v148 quad_perm:[2,3,0,1] row_mask:0xf bank_mask:0xf bound_ctrl:1
	v_cndmask_b32_e64 v211, v203, v202, s[10:11]
	v_add_f32_dpp v149, v149, v149 quad_perm:[2,3,0,1] row_mask:0xf bank_mask:0xf bound_ctrl:1
	v_pk_fma_f32 v[138:139], v[18:19], v[34:35], v[138:139]
	v_add_f32_dpp v212, v209, v208 quad_perm:[1,0,3,2] row_mask:0xf bank_mask:0xf bound_ctrl:1
	v_add_f32_dpp v148, v148, v148 row_half_mirror row_mask:0xf bank_mask:0xf bound_ctrl:1
	v_add_f32_dpp v149, v149, v149 row_half_mirror row_mask:0xf bank_mask:0xf bound_ctrl:1
	v_add_f32_dpp v213, v211, v210 quad_perm:[1,0,3,2] row_mask:0xf bank_mask:0xf bound_ctrl:1
	ds_read_b128 v[84:87], v29 offset:38448
	ds_read_b128 v[104:107], v29 offset:39728
	ds_read_b128 v[80:83], v29 offset:38432
	ds_read_b128 v[72:75], v29 offset:38400
	ds_read_b128 v[88:91], v29 offset:38464
	ds_read_b128 v[100:103], v29 offset:39712
	ds_read_b128 v[92:95], v29 offset:39680
	ds_read_b128 v[76:79], v29 offset:38416
	ds_read_b128 v[108:111], v29 offset:39744
	ds_read_b128 v[96:99], v29 offset:39696
	s_waitcnt lgkmcnt(10)
	v_pk_mul_f32 v[140:141], v[116:117], v[60:61] op_sel:[1,0] op_sel_hi:[1,1]
	v_cndmask_b32_e64 v214, v212, v213, s[14:15]
	v_add_f32_dpp v148, v148, v148 row_mirror row_mask:0xf bank_mask:0xf bound_ctrl:1
	v_add_f32_dpp v149, v149, v149 row_mirror row_mask:0xf bank_mask:0xf bound_ctrl:1
	v_cndmask_b32_e64 v215, v213, v212, s[14:15]
	v_pk_mul_f32 v[142:143], v[116:117], v[62:63] op_sel:[1,0] op_sel_hi:[1,1]
	v_fmac_f32_e32 v149, v116, v126
	v_add_f32_dpp v216, v215, v214 quad_perm:[2,3,0,1] row_mask:0xf bank_mask:0xf bound_ctrl:1
	v_pk_fma_f32 v[16:17], v[48:49], v[148:149], v[136:137] op_sel_hi:[1,0,1]
	v_pk_fma_f32 v[18:19], v[50:51], v[148:149], v[138:139] op_sel_hi:[1,0,1]
	v_add_f32_dpp v216, v216, v216 row_ror:8 row_mask:0xf bank_mask:0xf bound_ctrl:1
	v_pk_fma_f32 v[140:141], v[16:17], v[52:53], v[140:141]
	v_pk_mul_f32 v[144:145], v[16:17], v[36:37]
	v_add_f32_dpp v216, v216, v216 row_ror:4 row_mask:0xf bank_mask:0xf bound_ctrl:1
	v_pk_fma_f32 v[142:143], v[18:19], v[54:55], v[142:143]
	v_pk_fma_f32 v[144:145], v[18:19], v[38:39], v[144:145]
	v_cndmask_b32_e64 v28, v28, v216, s[42:43]
	v_pk_fma_f32 v[16:17], v[68:69], v[148:149], v[140:141] op_sel:[0,1,0] op_sel_hi:[1,1,1]
	v_pk_fma_f32 v[18:19], v[70:71], v[148:149], v[142:143] op_sel:[0,1,0] op_sel_hi:[1,1,1]
	v_pk_mul_f32 v[146:147], v[16:17], v[56:57]
	v_pk_fma_f32 v[146:147], v[18:19], v[58:59], v[146:147]
	s_waitcnt lgkmcnt(6)
	v_pk_mul_f32 v[132:133], v[16:17], v[84:85]
	v_pk_mul_f32 v[134:135], v[16:17], v[104:105]
	v_add_f32_e32 v204, v144, v145
	v_pk_fma_f32 v[132:133], v[18:19], v[86:87], v[132:133]
	v_pk_fma_f32 v[134:135], v[18:19], v[106:107], v[134:135]
	v_add_f32_e32 v205, v146, v147
	v_pk_mul_f32 v[136:137], v[118:119], v[80:81] op_sel_hi:[0,1]
	v_add_f32_e32 v148, v132, v133
	v_add_f32_e32 v149, v134, v135
	v_pk_mul_f32 v[138:139], v[118:119], v[82:83] op_sel_hi:[0,1]
	v_add_f32_dpp v148, v148, v148 quad_perm:[1,0,3,2] row_mask:0xf bank_mask:0xf bound_ctrl:1
	v_add_f32_dpp v149, v149, v149 quad_perm:[1,0,3,2] row_mask:0xf bank_mask:0xf bound_ctrl:1
	v_pk_fma_f32 v[136:137], v[16:17], v[72:73], v[136:137]
	v_add_f32_dpp v148, v148, v148 quad_perm:[2,3,0,1] row_mask:0xf bank_mask:0xf bound_ctrl:1
	v_add_f32_dpp v149, v149, v149 quad_perm:[2,3,0,1] row_mask:0xf bank_mask:0xf bound_ctrl:1
	v_pk_fma_f32 v[138:139], v[18:19], v[74:75], v[138:139]
	v_add_f32_dpp v148, v148, v148 row_half_mirror row_mask:0xf bank_mask:0xf bound_ctrl:1
	v_add_f32_dpp v149, v149, v149 row_half_mirror row_mask:0xf bank_mask:0xf bound_ctrl:1
	s_waitcnt lgkmcnt(0)
	v_pk_mul_f32 v[140:141], v[118:119], v[100:101] op_sel:[1,0] op_sel_hi:[1,1]
	v_add_f32_dpp v148, v148, v148 row_mirror row_mask:0xf bank_mask:0xf bound_ctrl:1
	v_add_f32_dpp v149, v149, v149 row_mirror row_mask:0xf bank_mask:0xf bound_ctrl:1
	v_pk_mul_f32 v[142:143], v[118:119], v[102:103] op_sel:[1,0] op_sel_hi:[1,1]
	v_fmac_f32_e32 v149, v118, v127
	v_pk_fma_f32 v[16:17], v[88:89], v[148:149], v[136:137] op_sel_hi:[1,0,1]
	v_pk_fma_f32 v[18:19], v[90:91], v[148:149], v[138:139] op_sel_hi:[1,0,1]
	v_pk_fma_f32 v[140:141], v[16:17], v[92:93], v[140:141]
	v_pk_mul_f32 v[144:145], v[16:17], v[76:77]
	v_pk_fma_f32 v[142:143], v[18:19], v[94:95], v[142:143]
	v_pk_fma_f32 v[144:145], v[18:19], v[78:79], v[144:145]
	v_pk_fma_f32 v[16:17], v[108:109], v[148:149], v[140:141] op_sel:[0,1,0] op_sel_hi:[1,1,1]
	v_pk_fma_f32 v[18:19], v[110:111], v[148:149], v[142:143] op_sel:[0,1,0] op_sel_hi:[1,1,1]
	v_pk_mul_f32 v[146:147], v[16:17], v[96:97]
	v_pk_fma_f32 v[146:147], v[18:19], v[98:99], v[146:147]
	s_waitcnt lgkmcnt(0)
	s_mov_b64 exec, 1
	ds_add_u32 v221, v222
	s_mov_b64 exec, -1
	ds_read_b128 v[224:227], v220
	s_mov_b32 s33, 0
	s_cmpk_eq_i32 s58, 0x7f
	s_cbranch_scc1 .Lpf_no0
	s_waitcnt lgkmcnt(0)
	v_min3_u32 v228, v224, v225, v226
	v_min_u32_e32 v228, v228, v227
	s_nop 0
	v_readfirstlane_b32 s41, v228
	s_add_u32 s40, s58, 1
	s_cmp_ge_u32 s41, s40
	s_cbranch_scc0 .Lpf_no0
	s_xor_b32 s54, s54, 1
	s_mul_i32 s40, s54, 0xa000
	s_mul_i32 s41, s54, 0xa00
	s_add_i32 s41, s41, 0x14000
	v_add_u32_e32 v29, s40, v24
	v_add_u32_e32 v31, v23, v22
	v_mul_u32_u24_e32 v31, 0x90, v31
	v_mov_b32_e32 v30, s41
	v_add_u32_e32 v31, s41, v31
	ds_read_b128 v[44:47], v29 offset:48
	ds_read_b128 v[64:67], v29 offset:1328
	ds_read_b128 v[40:43], v29 offset:32
	ds_read_b128 v[112:115], v31 offset:0
	ds_read_b128 v[32:35], v29 offset:0
	ds_read_b128 v[120:123], v30 offset:2304
	ds_read_b128 v[48:51], v29 offset:64
	ds_read_b128 v[60:63], v29 offset:1312
	ds_read_b128 v[52:55], v29 offset:1280
	ds_read_b128 v[36:39], v29 offset:16
	ds_read_b128 v[68:71], v29 offset:1344
	ds_read_b128 v[56:59], v29 offset:1296
	s_mov_b32 s33, 1
.Lpf_no0:
.LBB0_498:
	s_andn2_saveexec_b64 s[52:53], s[52:53]
	s_cbranch_execz .LBB0_495
	s_cmpk_eq_i32 s58, 0x7f
	s_cbranch_scc1 .LBB0_495
	v_lshl_add_u64 v[14:15], v[8:9], 0, s[28:29]
	global_load_dwordx4 v[30:33], v[14:15], off
	v_lshl_add_u64 v[14:15], v[10:11], 0, s[28:29]
	v_add_co_u32_e32 v34, vcc, 0xd504000, v14
	v_lshl_add_u64 v[38:39], v[6:7], 0, s[28:29]
	s_nop 0
	v_addc_co_u32_e32 v35, vcc, 0, v15, vcc
	global_load_dwordx2 v[44:45], v[34:35], off
	v_add_co_u32_e32 v34, vcc, s60, v38
	s_xor_b32 s11, s54, 1
	s_nop 0
	v_addc_co_u32_e32 v35, vcc, 0, v39, vcc
	global_load_dwordx2 v[40:41], v[34:35], off
	v_add_co_u32_e32 v34, vcc, s61, v38
	s_mul_i32 s15, s11, 0xa000
	s_nop 0
	v_addc_co_u32_e32 v35, vcc, 0, v39, vcc
	global_load_dwordx2 v[46:47], v[34:35], off
	v_add_co_u32_e32 v34, vcc, 0xdd04000, v14
	s_add_i32 s15, s15, 0
	s_nop 0
	v_addc_co_u32_e32 v35, vcc, 0, v15, vcc
	global_load_dwordx2 v[48:49], v[34:35], off
	v_add_co_u32_e32 v34, vcc, 0xe504000, v14
	v_add_u32_e32 v29, s15, v21
	s_nop 0
	v_addc_co_u32_e32 v35, vcc, 0, v15, vcc
	v_add_co_u32_e32 v14, vcc, 0xed04000, v14
	global_load_dwordx2 v[50:51], v[34:35], off
	s_nop 0
	v_addc_co_u32_e32 v15, vcc, 0, v15, vcc
	v_add_co_u32_e32 v42, vcc, s62, v38
	global_load_dwordx2 v[14:15], v[14:15], off
	s_nop 0
	v_addc_co_u32_e32 v43, vcc, 0, v39, vcc
	v_add_co_u32_e32 v38, vcc, s63, v38
	v_lshl_add_u64 v[34:35], v[4:5], 0, s[28:29]
	global_load_dwordx2 v[52:53], v[42:43], off
	v_addc_co_u32_e32 v39, vcc, 0, v39, vcc
	global_load_dwordx4 v[34:37], v[34:35], off
	s_mulk_i32 s11, 0xa00
	global_load_dwordx2 v[54:55], v[38:39], off
	s_add_i32 s11, s11, 0
	v_add_u32_e32 v56, s15, v20
	s_add_i32 s11, s11, 0x14000
	v_mov_b32_e32 v57, 0x1f010
	s_movk_i32 s33, 0x4000
